# comb17 + the mix-in phase's rstd loads also issued ahead of its second tile batch
# baseline (speedup 1.0000x reference)
; #define PG8_STAGE(bufoff, gbase, voff) do { _Pragma("unroll") for (int _i = 0; _i < 2; ++_i) \
;         __builtin_amdgcn_global_load_lds((const unsigned*)((const char*)(gbase) + (voff)[_i]), (LAS unsigned*)(lds + (bufoff) + ldsw + _i * 8192), 16, 0, 0); } while (0)
; #define PG8_WAIT_V(n) asm volatile("s_waitcnt vmcnt(" #n ")" ::: "memory")
; #define PG8_BAR __builtin_amdgcn_s_barrier()
; __device__ __forceinline__ void load_rstd(const float* part, int row0, int fq, float (&rs)[2][4]) {
; #pragma unroll
;     for (int ai = 0; ai < 2; ++ai)
; #pragma unroll
;         for (int m = 0; m < 4; ++m) { const float* p = part + (size_t)(row0 + ai * HALF + m * 16) * NPART + fq * 8;
;             const f32x4 a = *(const f32x4*)p, b = *(const f32x4*)(p + 4); float s = ((a[0] + a[1]) + (a[2] + a[3])) + ((b[0] + b[1]) + (b[2] + b[3]));
;             s += __shfl_xor(s, 16); s += __shfl_xor(s, 32); rs[ai][m] = rsqrtf(s * (1.0f / D) + RMS_EPS); }
; template <class Epi, class Sched, bool ALIGN_EPI>
; __device__ __forceinline__ void gemm_phase(LAS unsigned char* lds, const Gemm g, const Sched& S, const Epi& E) {
;     ...
;     PG8_STAGE(PG8_SB(0, 0), cB, voffB); PG8_STAGE(PG8_SB(0, 1), cB + hB, voffB); PG8_STAGE(PG8_SA(0, 0), cA, voffA); PG8_STAGE(PG8_SA(0, 1), cA + hA, voffA);
;     if (wr == 1) PG8_BAR;
;     PG8_WAIT_V(2); PG8_BAR;
;     PG8_STAGE(PG8_SB(1, 0), cB + kstep, voffB); PG8_STAGE(PG8_SA(1, 0), cA + kstep, voffA); PG8_STAGE(PG8_SB(1, 1), cB + hB + kstep, voffB);
;     PG8_WAIT_V(6); PG8_BAR;
.LBB0_450:
	s_mov_b64 s[40:41], 0x80
	s_and_b32 s26, s3, 3
	s_add_i32 m0, s61, 0x18000
	v_lshl_add_u64 v[6:7], v[6:7], 0, s[40:41]
	s_lshl_b32 s3, s2, 13
	s_lshl_b32 s18, s26, 12
	s_waitcnt vmcnt(2)
	s_barrier
	v_readlane_b32 s100, v254, 8
	v_lshrrev_b32_e32 v168, 1, v220
	s_lshl_b32 s101, s97, 8
	s_lshl_b32 s98, s100, 5
	s_add_i32 s101, s101, s98
	v_add_u32_e32 v168, s101, v168
	v_and_b32_e32 v169, 1, v220
	v_lshlrev_b32_e32 v169, 6, v169
	v_lshl_add_u32 v168, v168, 7, v169
	s_add_u32 s98, s14, 0xc300000
	s_addc_u32 s99, s15, 0
	global_load_dwordx4 v[176:179], v168, s[98:99]
	global_load_dwordx4 v[182:185], v168, s[98:99] offset:16
	global_load_dwordx4 v[186:189], v168, s[98:99] offset:32
	global_load_dwordx4 v[190:193], v168, s[98:99] offset:48
	s_mov_b32 s99, 0
	global_load_lds_dwordx4 v[6:7], off
	v_lshl_add_u64 v[4:5], v[4:5], 0, s[40:41]
	s_add_i32 m0, s61, 0x1a000
	s_add_i32 s69, s61, 0x8000
	s_add_i32 s71, s61, 0xa000
	global_load_lds_dwordx4 v[4:5], off
	v_lshl_add_u64 v[0:1], v[0:1], 0, s[40:41]
	s_mov_b32 m0, s69
	s_add_u32 s4, s80, 0x80080
	global_load_lds_dwordx4 v[0:1], off
	v_lshl_add_u64 v[0:1], v[2:3], 0, s[40:41]
	s_mov_b32 m0, s71
	s_addc_u32 s5, s81, 0
	global_load_lds_dwordx4 v[0:1], off
	s_add_i32 m0, s61, 0x1c000
	v_lshl_add_u64 v[0:1], s[4:5], 0, v[138:139]
	global_load_lds_dwordx4 v[0:1], off
	v_lshl_add_u64 v[0:1], s[4:5], 0, v[142:143]
	s_add_i32 m0, s61, 0x1e000
	v_lshlrev_b32_e32 v4, 2, v221
	global_load_lds_dwordx4 v[0:1], off
	v_bfe_u32 v1, v221, 4, 2
	v_and_b32_e32 v0, 15, v221
	v_lshlrev_b32_e32 v3, 4, v1
	v_lshl_or_b32 v159, s2, 6, v0
	v_lshl_or_b32 v0, v0, 6, v3
	v_and_b32_e32 v4, 32, v4
	v_bitop3_b32 v5, v0, s3, v4 bitop3:0xde
	v_lshlrev_b32_e32 v0, 6, v221
	s_movk_i32 s2, 0x3c0
	v_and_or_b32 v0, v0, s2, v3
	v_lshlrev_b32_e32 v2, 3, v1
	v_bitop3_b32 v165, s18, v0, v4 bitop3:0xf6
	v_cmp_eq_u32_e64 s[2:3], 0, v1
	v_lshlrev_b32_e32 v0, 5, v1
	v_mov_b32_e32 v1, v144
	v_lshl_add_u64 v[146:147], s[48:49], 0, v[0:1]
	v_lshlrev_b32_e32 v0, 9, v221
	v_and_b32_e32 v0, 0x70000, v0
	v_lshlrev_b32_e32 v1, 12, v10
	v_or3_b32 v0, v8, v0, v1
	v_add_u32_e32 v148, v0, v9
	v_lshlrev_b32_e32 v0, 5, v11
	v_and_b32_e32 v0, 0xf0000, v0
	s_waitcnt vmcnt(6)
	s_cmpk_lt_u32 s11, 0x100
	v_or3_b32 v0, v8, v0, v1
	s_cselect_b64 s[42:43], -1, 0
	v_add_u32_e32 v150, v0, v9
	s_add_i32 s92, 0, 0x10000
	s_add_i32 s93, 0, 0x14000
	v_mbcnt_lo_u32_b32 v0, -1, 0
	s_mov_b32 s27, s23
	s_ashr_i32 s73, s34, 31
	s_mov_b32 s90, s34
	s_ashr_i32 s91, s10, 31
	v_lshl_or_b32 v167, s26, 5, v2
	v_mov_b32_e32 v149, v144
	v_mov_b32_e32 v151, v144
	v_mov_b64_e32 v[152:153], 0x200
	v_mov_b64_e32 v[154:155], 0x1ff
	v_add_u32_e32 v173, s92, v165
	v_add_u32_e32 v175, s93, v165
	v_add_u32_e32 v181, 0, v5
	v_mbcnt_hi_u32_b32 v222, -1, v0
	s_mov_b32 s58, 0x3a000000
	s_mov_b32 s94, 0x800000
	s_mov_b32 s60, 0x3e6d3388
	s_mov_b32 s62, 0x3f07dc22
	s_mov_b32 s64, 0xbf3a00e3
	s_mov_b32 s66, 0x3f35f0e3
	s_mov_b32 s68, 0xbe11a98e
	s_mov_b32 s70, 0x3e027906
	s_mov_b32 s72, 0xbf38aa3b
	s_mov_b32 s95, 0
	s_barrier
	v_mov_b32_e32 v169, 0x358637bd
	s_nop 0
	v_add_f32_e32 v176, v176, v177
	v_add_f32_e32 v178, v178, v179
	v_add_f32_e32 v182, v182, v183
	v_add_f32_e32 v184, v184, v185
	v_add_f32_e32 v186, v186, v187
	v_add_f32_e32 v188, v188, v189
	v_add_f32_e32 v190, v190, v191
	v_add_f32_e32 v192, v192, v193
	v_add_f32_e32 v176, v176, v178
	v_add_f32_e32 v182, v182, v184
	v_add_f32_e32 v186, v186, v188
	v_add_f32_e32 v190, v190, v192
	v_add_f32_e32 v176, v176, v182
	v_add_f32_e32 v186, v186, v190
	v_add_f32_e32 v176, v176, v186
	s_nop 1
	v_add_f32_dpp v182, v176, v176 quad_perm:[1,0,3,2] row_mask:0xf bank_mask:0xf
	v_fmamk_f32 v182, v182, 0x3a000000, v169
	v_rsq_f32_e32 v182, v182
	s_lshl_b32 s101, s100, 7
	s_add_i32 s101, s101, 0x21000
	v_lshrrev_b32_e32 v168, 1, v220
	v_lshl_add_u32 v168, v168, 2, s101
	ds_write_b32 v168, v182
	s_branch .LBB0_453
